# phase A weight-transpose loop: first-half vmcnt waits no longer drain the previous tile's two stores (preheader drains instead)
# baseline (speedup 1.0000x reference)
.LBB0_82:
	v_mov_b32_e32 v2, v200
	s_ashr_i32 s61, s60, 31
	v_ashrrev_i32_e32 v0, 5, v2
	v_add_u32_e32 v10, s42, v0
	v_lshlrev_b32_e32 v2, 4, v2
	v_mad_i64_i32 v[0:1], s[10:11], s38, v10, 0
	v_and_b32_e32 v168, 0x1f0, v2
	v_add_u32_e32 v2, 16, v10
	v_add_u32_e32 v8, 32, v10
	v_add_u32_e32 v10, 48, v10
	v_mad_i64_i32 v[2:3], s[12:13], s38, v2, 0
	v_mad_i64_i32 v[8:9], s[12:13], s38, v8, 0
	v_mad_i64_i32 v[10:11], s[12:13], s38, v10, 0
	v_lshl_add_u64 v[0:1], v[0:1], 2, s[40:41]
	s_lshl_b64 s[10:11], s[60:61], 2
	v_lshl_add_u64 v[2:3], v[2:3], 2, s[40:41]
	v_lshl_add_u64 v[8:9], v[8:9], 2, s[40:41]
	v_lshl_add_u64 v[10:11], v[10:11], 2, s[40:41]
	v_lshl_add_u64 v[0:1], v[0:1], 0, s[10:11]
	v_lshl_add_u64 v[2:3], v[2:3], 0, s[10:11]
	v_lshl_add_u64 v[8:9], v[8:9], 0, s[10:11]
	v_lshl_add_u64 v[10:11], v[10:11], 0, s[10:11]
	v_lshl_add_u64 v[0:1], v[0:1], 0, v[168:169]
	v_lshl_add_u64 v[4:5], v[2:3], 0, v[168:169]
	v_lshl_add_u64 v[8:9], v[8:9], 0, v[168:169]
	s_waitcnt vmcnt(12)
	v_lshl_add_u64 v[12:13], v[10:11], 0, v[168:169]
	global_load_dwordx4 v[0:3], v[0:1], off
	s_nop 0
	global_load_dwordx4 v[4:7], v[4:5], off
	s_nop 0
	global_load_dwordx4 v[8:11], v[8:9], off
	s_nop 0
	global_load_dwordx4 v[12:15], v[12:13], off
	s_add_u32 s48, s58, s7
	s_addc_u32 s49, s59, 0
	s_add_u32 s58, s66, s8
	s_addc_u32 s59, s67, 0
	s_waitcnt vmcnt(0)
	s_branch .LBB0_85

.LBB0_93:
	s_waitcnt vmcnt(11)
	v_mov_b32_e32 v32, v200
	s_andn2_b64 vcc, exec, s[78:79]
	v_lshlrev_b32_e32 v34, 2, v32
	v_ashrrev_i32_e32 v33, 5, v32
	v_and_b32_e32 v34, 0x7c, v34
	v_mul_u32_u24_e32 v34, 0x104, v34
	v_lshlrev_b32_e32 v33, 2, v33
	v_add3_u32 v33, 0, v34, v33
	v_cndmask_b32_e64 v34, 0, 1, s[78:79]
	v_cmp_ne_u32_e64 s[40:41], 1, v34
	s_barrier
	s_waitcnt vmcnt(4)
	ds_write2_b32 v33, v0, v4 offset1:16
	ds_write2_b32 v33, v1, v5 offset0:65 offset1:81
	ds_write2_b32 v33, v2, v6 offset0:130 offset1:146
	ds_write2_b32 v33, v3, v7 offset0:195 offset1:211
	s_waitcnt vmcnt(2)
	ds_write2_b32 v33, v8, v12 offset0:32 offset1:48
	ds_write2_b32 v33, v9, v13 offset0:97 offset1:113
	ds_write2_b32 v33, v10, v14 offset0:162 offset1:178
	ds_write2_b32 v33, v11, v15 offset0:227 offset1:243
	s_cbranch_vccnz .LBB0_95
	v_mov_b32_e32 v18, v200
	s_ashr_i32 s75, s74, 31
	v_ashrrev_i32_e32 v16, 5, v18
	v_add_u32_e32 v26, s72, v16
	v_lshlrev_b32_e32 v18, 4, v18
	v_mad_i64_i32 v[16:17], s[8:9], s38, v26, 0
	v_and_b32_e32 v168, 0x1f0, v18
	v_add_u32_e32 v18, 16, v26
	v_add_u32_e32 v24, 32, v26
	v_add_u32_e32 v26, 48, v26
	v_mad_i64_i32 v[18:19], s[10:11], s38, v18, 0
	v_mad_i64_i32 v[24:25], s[10:11], s38, v24, 0
	v_mad_i64_i32 v[26:27], s[10:11], s38, v26, 0
	v_lshl_add_u64 v[16:17], v[16:17], 2, s[76:77]
	s_lshl_b64 s[8:9], s[74:75], 2
	v_lshl_add_u64 v[18:19], v[18:19], 2, s[76:77]
	v_lshl_add_u64 v[24:25], v[24:25], 2, s[76:77]
	v_lshl_add_u64 v[26:27], v[26:27], 2, s[76:77]
	v_lshl_add_u64 v[16:17], v[16:17], 0, s[8:9]
	v_lshl_add_u64 v[18:19], v[18:19], 0, s[8:9]
	v_lshl_add_u64 v[24:25], v[24:25], 0, s[8:9]
	v_lshl_add_u64 v[26:27], v[26:27], 0, s[8:9]
	v_lshl_add_u64 v[16:17], v[16:17], 0, v[168:169]
	v_lshl_add_u64 v[18:19], v[18:19], 0, v[168:169]
	v_lshl_add_u64 v[24:25], v[24:25], 0, v[168:169]
	v_lshl_add_u64 v[26:27], v[26:27], 0, v[168:169]
	global_load_dwordx4 v[20:23], v[16:17], off
	s_nop 0
	global_load_dwordx4 v[16:19], v[18:19], off
	s_nop 0
	global_load_dwordx4 v[28:31], v[24:25], off
	s_nop 0
	global_load_dwordx4 v[24:27], v[26:27], off
